# residual stream x (read back only by the same workgroup) stored write-back instead of write-through in the post phases
# speedup vs baseline: 1.0042x; 1.0042x over previous
.LBB0_21:
	s_or_b64 exec, exec, s[14:15]
	s_waitcnt vmcnt(7)
	v_mul_f32_e32 v2, v35, v35
	v_fmac_f32_e32 v2, v34, v34
	v_fmac_f32_e32 v2, v36, v36
	v_fmac_f32_e32 v2, v37, v37
	s_waitcnt vmcnt(6)
	v_fmac_f32_e32 v2, v30, v30
	v_fmac_f32_e32 v2, v31, v31
	v_fmac_f32_e32 v2, v32, v32
	v_fmac_f32_e32 v2, v33, v33
	s_waitcnt vmcnt(5)
	v_fmac_f32_e32 v2, v10, v10
	v_fmac_f32_e32 v2, v11, v11
	v_fmac_f32_e32 v2, v12, v12
	v_fmac_f32_e32 v2, v13, v13
	s_waitcnt vmcnt(4)
	v_fmac_f32_e32 v2, v6, v6
	v_fmac_f32_e32 v2, v7, v7
	v_pk_mul_f32 v[4:5], v[8:9], v[8:9]
	global_store_dwordx4 v[94:95], v[34:37], off
	global_store_dwordx4 v[94:95], v[30:33], off offset:1024
	global_store_dwordx4 v[94:95], v[10:13], off offset:2048
	global_store_dwordx4 v[94:95], v[6:9], off offset:3072
	v_add_f32_e32 v2, v4, v2
	v_add_f32_e32 v2, v5, v2
	v_add_u32_e32 v86, s6, v86
	s_movk_i32 s0, 0x3fff
	v_add_f32_dpp v2, v2, v2 row_ror:1 row_mask:0xf bank_mask:0xf bound_ctrl:1
	v_lshl_add_u64 v[92:93], v[92:93], 0, s[6:7]
	v_lshl_add_u64 v[94:95], v[94:95], 0, s[10:11]
	v_add_f32_dpp v2, v2, v2 row_ror:2 row_mask:0xf bank_mask:0xf bound_ctrl:1
	s_nop 1
	v_add_f32_dpp v2, v2, v2 row_ror:4 row_mask:0xf bank_mask:0xf bound_ctrl:1
	s_nop 1
	v_add_f32_dpp v2, v2, v2 row_ror:8 row_mask:0xf bank_mask:0xf bound_ctrl:1
	ds_bpermute_b32 v4, v96, v2
	s_waitcnt lgkmcnt(0)
	v_add_f32_e32 v2, v2, v4
	v_mov_b32_e32 v4, v2
	s_nop 1
	v_permlane32_swap_b32 v2, v4
	s_nop 1
	s_nop 0
	v_add_f32_e32 v2, v2, v4
	v_fmamk_f32 v2, v2, 0x3a800000, v1
	v_mul_f32_e32 v4, 0x4b800000, v2
	v_cmp_gt_f32_e32 vcc, s91, v2
	s_nop 1
	v_cndmask_b32_e32 v2, v2, v4, vcc
	v_rsq_f32_e32 v2, v2
	s_nop 0
	v_mul_f32_e32 v4, 0x45800000, v2
	v_cndmask_b32_e32 v2, v2, v4, vcc
	v_pk_mul_f32 v[4:5], v[34:35], v[2:3] op_sel_hi:[1,0]
	s_waitcnt vmcnt(7)
	v_pk_add_f32 v[34:35], v[54:55], 1.0 op_sel_hi:[1,0]
	s_waitcnt vmcnt(4)
	v_pk_mul_f32 v[4:5], v[26:27], v[4:5]
	v_cmp_lt_i32_e32 vcc, s0, v86
	v_pk_fma_f32 v[4:5], v[34:35], v[4:5], v[50:51]
	v_pk_mul_f32 v[34:35], v[36:37], v[2:3] op_sel_hi:[1,0]
	v_pk_add_f32 v[36:37], v[56:57], 1.0 op_sel_hi:[1,0]
	v_pk_mul_f32 v[34:35], v[28:29], v[34:35]
	v_cvt_pk_bf16_f32 v4, v4, v5
	v_pk_fma_f32 v[34:35], v[36:37], v[34:35], v[52:53]
	s_or_b64 s[12:13], vcc, s[12:13]
	v_cvt_pk_bf16_f32 v5, v34, v35
	global_store_dwordx2 v[90:91], v[4:5], off sc1
	v_pk_mul_f32 v[4:5], v[30:31], v[2:3] op_sel_hi:[1,0]
	v_pk_add_f32 v[30:31], v[42:43], 1.0 op_sel_hi:[1,0]
	v_pk_mul_f32 v[4:5], v[22:23], v[4:5]
	v_mov_b64_e32 v[34:35], v[62:63]
	v_pk_fma_f32 v[4:5], v[30:31], v[4:5], v[58:59]
	v_pk_mul_f32 v[30:31], v[32:33], v[2:3] op_sel_hi:[1,0]
	v_pk_add_f32 v[32:33], v[44:45], 1.0 op_sel_hi:[1,0]
	v_pk_mul_f32 v[30:31], v[24:25], v[30:31]
	v_cvt_pk_bf16_f32 v4, v4, v5
	v_pk_fma_f32 v[30:31], v[32:33], v[30:31], v[60:61]
	v_mov_b64_e32 v[36:37], v[64:65]
	v_cvt_pk_bf16_f32 v5, v30, v31
	global_store_dwordx2 v[90:91], v[4:5], off offset:512 sc1
	v_pk_mul_f32 v[4:5], v[10:11], v[2:3] op_sel_hi:[1,0]
	v_pk_add_f32 v[10:11], v[38:39], 1.0 op_sel_hi:[1,0]
	v_pk_mul_f32 v[4:5], v[18:19], v[4:5]
	v_mov_b64_e32 v[30:31], v[66:67]
	v_pk_fma_f32 v[4:5], v[10:11], v[4:5], v[74:75]
	v_pk_mul_f32 v[10:11], v[12:13], v[2:3] op_sel_hi:[1,0]
	v_pk_add_f32 v[12:13], v[40:41], 1.0 op_sel_hi:[1,0]
	v_pk_mul_f32 v[10:11], v[20:21], v[10:11]
	v_cvt_pk_bf16_f32 v4, v4, v5
	v_pk_fma_f32 v[10:11], v[12:13], v[10:11], v[76:77]
	v_mov_b64_e32 v[32:33], v[68:69]
	v_cvt_pk_bf16_f32 v5, v10, v11
	global_store_dwordx2 v[90:91], v[4:5], off offset:1024 sc1
	v_pk_mul_f32 v[4:5], v[6:7], v[2:3] op_sel_hi:[1,0]
	v_pk_add_f32 v[6:7], v[46:47], 1.0 op_sel_hi:[1,0]
	v_pk_mul_f32 v[4:5], v[14:15], v[4:5]
	v_mov_b64_e32 v[10:11], v[78:79]
	v_pk_fma_f32 v[4:5], v[6:7], v[4:5], v[70:71]
	v_pk_mul_f32 v[6:7], v[8:9], v[2:3] op_sel_hi:[1,0]
	v_pk_add_f32 v[8:9], v[48:49], 1.0 op_sel_hi:[1,0]
	v_pk_mul_f32 v[6:7], v[16:17], v[6:7]
	v_cvt_pk_bf16_f32 v4, v4, v5
	v_pk_fma_f32 v[6:7], v[8:9], v[6:7], v[72:73]
	v_mov_b64_e32 v[12:13], v[80:81]
	v_cvt_pk_bf16_f32 v5, v6, v7
	v_mov_b64_e32 v[6:7], v[82:83]
	global_store_dwordx2 v[90:91], v[4:5], off offset:1536 sc1
	v_lshl_add_u64 v[90:91], v[90:91], 0, s[8:9]
	v_mov_b64_e32 v[8:9], v[84:85]
	s_andn2_b64 exec, exec, s[12:13]
	s_cbranch_execz .LBB0_29

.LBB0_274:
	s_or_b64 exec, exec, s[14:15]
	v_lshlrev_b32_e32 v150, 16, v142
	v_and_b32_e32 v151, 0xffff0000, v142
	v_lshlrev_b32_e32 v158, 16, v140
	v_and_b32_e32 v159, 0xffff0000, v140
	v_and_b32_e32 v165, 0xffff0000, v136
	v_and_b32_e32 v167, 0xffff0000, v134
	v_pk_mul_f32 v[154:155], v[150:151], v[150:151]
	v_lshlrev_b32_e32 v142, 16, v143
	v_and_b32_e32 v143, 0xffff0000, v143
	v_pk_mul_f32 v[160:161], v[158:159], v[158:159]
	v_lshlrev_b32_e32 v140, 16, v141
	v_and_b32_e32 v141, 0xffff0000, v141
	v_lshlrev_b32_e32 v164, 16, v136
	v_lshlrev_b32_e32 v166, 16, v134
	v_mov_b32_e32 v170, v167
	v_mov_b32_e32 v171, v165
	v_pk_mul_f32 v[156:157], v[142:143], v[142:143]
	v_pk_mul_f32 v[162:163], v[140:141], v[140:141]
	v_lshlrev_b32_e32 v136, 16, v137
	v_lshlrev_b32_e32 v134, 16, v135
	v_mov_b32_e32 v168, v166
	v_mov_b32_e32 v169, v164
	v_pk_mul_f32 v[170:171], v[170:171], v[170:171]
	v_add_f32_e32 v154, v154, v155
	v_add_f32_e32 v155, v160, v161
	v_and_b32_e32 v137, 0xffff0000, v137
	v_and_b32_e32 v135, 0xffff0000, v135
	v_pk_fma_f32 v[168:169], v[168:169], v[168:169], v[170:171]
	v_mov_b32_e32 v170, v134
	v_mov_b32_e32 v171, v136
	v_add_f32_e32 v154, v156, v154
	v_add_f32_e32 v155, v162, v155
	v_mov_b32_e32 v172, v135
	v_mov_b32_e32 v173, v137
	v_pk_fma_f32 v[168:169], v[170:171], v[170:171], v[168:169]
	v_add_f32_e32 v154, v157, v154
	v_add_f32_e32 v155, v163, v155
	v_pk_fma_f32 v[168:169], v[172:173], v[172:173], v[168:169]
	v_add_f32_e32 v154, v155, v154
	v_add_f32_e32 v154, v169, v154
	v_add_f32_e32 v154, v168, v154
	v_lshl_add_u64 v[4:5], v[130:131], 0, v[120:121]
	s_mov_b32 s0, 0x6198000
	v_add_f32_dpp v154, v154, v154 row_ror:1 row_mask:0xf bank_mask:0xf bound_ctrl:1
	s_and_b64 s[2:3], exec, s[2:3]
	s_or_b64 s[12:13], s[2:3], s[12:13]
	v_add_f32_dpp v154, v154, v154 row_ror:2 row_mask:0xf bank_mask:0xf bound_ctrl:1
	v_lshl_add_u64 v[128:129], v[128:129], 0, s[10:11]
	v_lshl_add_u64 v[130:131], v[130:131], 0, s[10:11]
	v_add_f32_dpp v154, v154, v154 row_ror:4 row_mask:0xf bank_mask:0xf bound_ctrl:1
	v_lshl_add_u64 v[132:133], v[132:133], 0, s[8:9]
	s_nop 0
	v_add_f32_dpp v154, v154, v154 row_ror:8 row_mask:0xf bank_mask:0xf bound_ctrl:1
	ds_bpermute_b32 v155, v152, v154
	s_waitcnt lgkmcnt(0)
	v_add_f32_e32 v154, v154, v155
	v_mov_b32_e32 v155, v154
	s_nop 1
	v_permlane32_swap_b32 v155, v154
	s_nop 1
	s_nop 0
	v_add_f32_e32 v154, v155, v154
	v_fmamk_f32 v154, v154, 0x3a800000, v1
	v_cmp_gt_f32_e32 vcc, s91, v154
	v_mul_f32_e32 v155, 0x4b800000, v154
	s_nop 0
	v_cndmask_b32_e32 v154, v154, v155, vcc
	v_rsq_f32_e32 v154, v154
	s_nop 0
	v_mul_f32_e32 v155, 0x45800000, v154
	v_cndmask_b32_e32 v154, v154, v155, vcc
	v_pk_mul_f32 v[142:143], v[154:155], v[142:143] op_sel_hi:[0,1]
	v_pk_mul_f32 v[140:141], v[154:155], v[140:141] op_sel_hi:[0,1]
	v_pk_mul_f32 v[136:137], v[154:155], v[136:137] op_sel_hi:[0,1]
	v_pk_mul_f32 v[150:151], v[154:155], v[150:151] op_sel_hi:[0,1]
	v_pk_mul_f32 v[142:143], v[36:37], v[142:143]
	v_pk_mul_f32 v[140:141], v[28:29], v[140:141]
	v_pk_mul_f32 v[136:137], v[20:21], v[136:137]
	v_pk_mul_f32 v[150:151], v[34:35], v[150:151]
	s_waitcnt vmcnt(9)
	v_pk_fma_f32 v[44:45], v[76:77], v[142:143], v[44:45]
	v_pk_mul_f32 v[142:143], v[154:155], v[158:159] op_sel_hi:[0,1]
	s_waitcnt vmcnt(8)
	v_pk_fma_f32 v[48:49], v[72:73], v[140:141], v[48:49]
	v_pk_mul_f32 v[140:141], v[154:155], v[164:165] op_sel_hi:[0,1]
	s_waitcnt vmcnt(5)
	v_pk_fma_f32 v[52:53], v[84:85], v[136:137], v[52:53]
	v_pk_mul_f32 v[136:137], v[154:155], v[166:167] op_sel_hi:[0,1]
	v_pk_mul_f32 v[134:135], v[154:155], v[134:135] op_sel_hi:[0,1]
	v_pk_fma_f32 v[42:43], v[74:75], v[150:151], v[42:43]
	v_pk_mul_f32 v[142:143], v[26:27], v[142:143]
	v_pk_mul_f32 v[140:141], v[18:19], v[140:141]
	v_pk_mul_f32 v[136:137], v[10:11], v[136:137]
	v_pk_mul_f32 v[134:135], v[12:13], v[134:135]
	v_pk_fma_f32 v[46:47], v[70:71], v[142:143], v[46:47]
	v_pk_fma_f32 v[50:51], v[82:83], v[140:141], v[50:51]
	s_waitcnt vmcnt(4)
	v_pk_fma_f32 v[38:39], v[86:87], v[136:137], v[38:39]
	v_pk_fma_f32 v[40:41], v[88:89], v[134:135], v[40:41]
	global_store_dwordx4 v[4:5], v[42:45], off
	global_store_dwordx4 v[4:5], v[46:49], off offset:1024
	global_store_dwordx4 v[4:5], v[50:53], off offset:2048
	global_store_dwordx4 v[4:5], v[38:41], off offset:3072
	v_pk_mul_f32 v[4:5], v[42:43], v[42:43]
	v_pk_mul_f32 v[134:135], v[44:45], v[44:45]
	v_add_f32_e32 v4, v4, v5
	v_add_f32_e32 v4, v134, v4
	v_pk_mul_f32 v[136:137], v[46:47], v[46:47]
	v_add_f32_e32 v4, v135, v4
	v_add_f32_e32 v4, v136, v4
	v_pk_mul_f32 v[140:141], v[48:49], v[48:49]
	v_add_f32_e32 v4, v137, v4
	v_add_f32_e32 v4, v140, v4
	v_pk_mul_f32 v[142:143], v[50:51], v[50:51]
	v_add_f32_e32 v4, v141, v4
	v_add_f32_e32 v4, v142, v4
	v_pk_mul_f32 v[150:151], v[52:53], v[52:53]
	v_add_f32_e32 v4, v143, v4
	v_add_f32_e32 v4, v150, v4
	v_pk_mul_f32 v[154:155], v[38:39], v[38:39]
	v_add_f32_e32 v4, v151, v4
	v_add_f32_e32 v4, v154, v4
	v_pk_mul_f32 v[156:157], v[40:41], v[40:41]
	v_add_f32_e32 v4, v155, v4
	v_add_f32_e32 v4, v156, v4
	v_add_f32_e32 v4, v157, v4
	v_pk_add_f32 v[136:137], v[78:79], 1.0 op_sel_hi:[1,0]
	v_lshl_add_u64 v[134:135], v[126:127], 0, v[124:125]
	v_add_f32_dpp v4, v4, v4 row_ror:1 row_mask:0xf bank_mask:0xf bound_ctrl:1
	v_lshl_add_u64 v[126:127], v[126:127], 0, s[8:9]
	s_waitcnt vmcnt(6)
	v_mov_b64_e32 v[140:141], v[146:147]
	v_add_f32_dpp v4, v4, v4 row_ror:2 row_mask:0xf bank_mask:0xf bound_ctrl:1
	v_mov_b64_e32 v[142:143], v[148:149]
	v_mov_b32_e32 v150, v2
	v_add_f32_dpp v4, v4, v4 row_ror:4 row_mask:0xf bank_mask:0xf bound_ctrl:1
	s_nop 1
	v_add_f32_dpp v4, v4, v4 row_ror:8 row_mask:0xf bank_mask:0xf bound_ctrl:1
	ds_bpermute_b32 v5, v152, v4
	s_waitcnt lgkmcnt(0)
	v_add_f32_e32 v4, v4, v5
	v_mov_b32_e32 v5, v4
	s_nop 1
	v_permlane32_swap_b32 v5, v4
	s_nop 1
	s_nop 0
	v_add_f32_e32 v4, v5, v4
	v_fmamk_f32 v4, v4, 0x3a800000, v1
	v_cmp_gt_f32_e32 vcc, s91, v4
	v_mul_f32_e32 v5, 0x4b800000, v4
	s_nop 0
	v_cndmask_b32_e32 v4, v4, v5, vcc
	v_rsq_f32_e32 v4, v4
	s_nop 0
	v_mul_f32_e32 v5, 0x45800000, v4
	v_cndmask_b32_e32 v4, v4, v5, vcc
	v_pk_mul_f32 v[42:43], v[42:43], v[4:5] op_sel_hi:[1,0]
	v_pk_mul_f32 v[44:45], v[44:45], v[4:5] op_sel_hi:[1,0]
	v_pk_mul_f32 v[42:43], v[30:31], v[42:43]
	v_pk_mul_f32 v[44:45], v[32:33], v[44:45]
	v_pk_fma_f32 v[42:43], v[136:137], v[42:43], v[98:99]
	v_pk_add_f32 v[136:137], v[80:81], 1.0 op_sel_hi:[1,0]
	v_cvt_pk_bf16_f32 v42, v42, v43
	v_pk_fma_f32 v[44:45], v[136:137], v[44:45], v[100:101]
	v_pk_mul_f32 v[38:39], v[38:39], v[4:5] op_sel_hi:[1,0]
	v_cvt_pk_bf16_f32 v43, v44, v45
	v_add_co_u32_e32 v44, vcc, s0, v134
	v_pk_mul_f32 v[38:39], v[6:7], v[38:39]
	s_nop 0
	v_addc_co_u32_e32 v45, vcc, 0, v135, vcc
	global_store_dwordx2 v[44:45], v[42:43], off sc1
	v_pk_mul_f32 v[42:43], v[46:47], v[4:5] op_sel_hi:[1,0]
	v_pk_add_f32 v[46:47], v[90:91], 1.0 op_sel_hi:[1,0]
	v_pk_mul_f32 v[42:43], v[22:23], v[42:43]
	s_waitcnt vmcnt(5)
	v_mov_b64_e32 v[134:135], v[138:139]
	v_pk_fma_f32 v[42:43], v[46:47], v[42:43], v[106:107]
	v_pk_mul_f32 v[46:47], v[48:49], v[4:5] op_sel_hi:[1,0]
	v_pk_add_f32 v[48:49], v[92:93], 1.0 op_sel_hi:[1,0]
	v_pk_mul_f32 v[46:47], v[24:25], v[46:47]
	v_cvt_pk_bf16_f32 v42, v42, v43
	v_pk_fma_f32 v[46:47], v[48:49], v[46:47], v[108:109]
	v_pk_add_f32 v[48:49], v[96:97], 1.0 op_sel_hi:[1,0]
	v_cvt_pk_bf16_f32 v43, v46, v47
	global_store_dwordx2 v[44:45], v[42:43], off offset:512 sc1
	v_pk_mul_f32 v[42:43], v[50:51], v[4:5] op_sel_hi:[1,0]
	v_pk_add_f32 v[46:47], v[94:95], 1.0 op_sel_hi:[1,0]
	v_pk_mul_f32 v[42:43], v[14:15], v[42:43]
	v_mov_b64_e32 v[136:137], v[144:145]
	v_pk_fma_f32 v[42:43], v[46:47], v[42:43], v[114:115]
	v_pk_mul_f32 v[46:47], v[52:53], v[4:5] op_sel_hi:[1,0]
	v_cvt_pk_bf16_f32 v42, v42, v43
	v_pk_mul_f32 v[46:47], v[16:17], v[46:47]
	v_pk_mul_f32 v[4:5], v[40:41], v[4:5] op_sel_hi:[1,0]
	v_pk_fma_f32 v[46:47], v[48:49], v[46:47], v[116:117]
	v_pk_mul_f32 v[4:5], v[8:9], v[4:5]
	v_cvt_pk_bf16_f32 v43, v46, v47
	global_store_dwordx2 v[44:45], v[42:43], off offset:1024 sc1
	v_pk_add_f32 v[42:43], v[102:103], 1.0 op_sel_hi:[1,0]
	v_pk_add_f32 v[40:41], v[104:105], 1.0 op_sel_hi:[1,0]
	v_pk_fma_f32 v[38:39], v[42:43], v[38:39], v[110:111]
	v_pk_fma_f32 v[4:5], v[40:41], v[4:5], v[112:113]
	v_cvt_pk_bf16_f32 v38, v38, v39
	v_cvt_pk_bf16_f32 v39, v4, v5
	global_store_dwordx2 v[44:45], v[38:39], off offset:1536 sc1
	v_mov_b64_e32 v[42:43], v[54:55]
	v_mov_b64_e32 v[46:47], v[58:59]
	v_mov_b64_e32 v[50:51], v[62:63]
	v_mov_b64_e32 v[38:39], v[66:67]
	v_mov_b64_e32 v[44:45], v[56:57]
	v_mov_b64_e32 v[48:49], v[60:61]
	v_mov_b64_e32 v[52:53], v[64:65]
	v_mov_b64_e32 v[40:41], v[68:69]
	s_andn2_b64 exec, exec, s[12:13]
	s_cbranch_execz .LBB0_279

.LBB0_641:
	s_or_b64 exec, exec, s[16:17]
	v_lshlrev_b32_e32 v154, 16, v146
	v_and_b32_e32 v155, 0xffff0000, v146
	v_lshlrev_b32_e32 v160, 16, v144
	v_and_b32_e32 v161, 0xffff0000, v144
	v_and_b32_e32 v167, 0xffff0000, v142
	v_and_b32_e32 v169, 0xffff0000, v140
	v_pk_mul_f32 v[156:157], v[154:155], v[154:155]
	v_lshlrev_b32_e32 v146, 16, v147
	v_and_b32_e32 v147, 0xffff0000, v147
	v_pk_mul_f32 v[162:163], v[160:161], v[160:161]
	v_lshlrev_b32_e32 v144, 16, v145
	v_and_b32_e32 v145, 0xffff0000, v145
	v_lshlrev_b32_e32 v166, 16, v142
	v_lshlrev_b32_e32 v168, 16, v140
	v_mov_b32_e32 v172, v169
	v_mov_b32_e32 v173, v167
	v_pk_mul_f32 v[158:159], v[146:147], v[146:147]
	v_pk_mul_f32 v[164:165], v[144:145], v[144:145]
	v_lshlrev_b32_e32 v142, 16, v143
	v_lshlrev_b32_e32 v140, 16, v141
	v_mov_b32_e32 v170, v168
	v_mov_b32_e32 v171, v166
	v_pk_mul_f32 v[172:173], v[172:173], v[172:173]
	v_add_f32_e32 v148, v156, v157
	v_add_f32_e32 v151, v162, v163
	v_and_b32_e32 v143, 0xffff0000, v143
	v_and_b32_e32 v141, 0xffff0000, v141
	v_pk_fma_f32 v[170:171], v[170:171], v[170:171], v[172:173]
	v_mov_b32_e32 v172, v140
	v_mov_b32_e32 v173, v142
	v_add_f32_e32 v148, v158, v148
	v_add_f32_e32 v151, v164, v151
	v_mov_b32_e32 v174, v141
	v_mov_b32_e32 v175, v143
	v_pk_fma_f32 v[170:171], v[172:173], v[172:173], v[170:171]
	v_add_f32_e32 v148, v159, v148
	v_add_f32_e32 v151, v165, v151
	v_pk_fma_f32 v[170:171], v[174:175], v[174:175], v[170:171]
	v_add_f32_e32 v148, v151, v148
	v_add_f32_e32 v148, v171, v148
	v_add_f32_e32 v148, v170, v148
	v_lshl_add_u64 v[152:153], v[128:129], 0, v[120:121]
	s_mov_b32 s0, 0x6198000
	v_add_f32_dpp v148, v148, v148 row_ror:1 row_mask:0xf bank_mask:0xf bound_ctrl:1
	s_and_b64 s[2:3], exec, s[2:3]
	s_or_b64 s[6:7], s[2:3], s[6:7]
	v_add_f32_dpp v148, v148, v148 row_ror:2 row_mask:0xf bank_mask:0xf bound_ctrl:1
	v_lshl_add_u64 v[4:5], v[4:5], 0, s[14:15]
	v_lshl_add_u64 v[128:129], v[128:129], 0, s[14:15]
	v_add_f32_dpp v148, v148, v148 row_ror:4 row_mask:0xf bank_mask:0xf bound_ctrl:1
	v_lshl_add_u64 v[138:139], v[138:139], 0, s[12:13]
	s_nop 0
	v_add_f32_dpp v148, v148, v148 row_ror:8 row_mask:0xf bank_mask:0xf bound_ctrl:1
	ds_bpermute_b32 v151, v149, v148
	s_waitcnt lgkmcnt(0)
	v_add_f32_e32 v148, v148, v151
	v_mov_b32_e32 v151, v148
	s_nop 1
	v_permlane32_swap_b32 v151, v148
	s_nop 1
	s_nop 0
	v_add_f32_e32 v148, v151, v148
	v_fmamk_f32 v148, v148, 0x3a800000, v1
	v_cmp_gt_f32_e32 vcc, s91, v148
	v_mul_f32_e32 v151, 0x4b800000, v148
	s_nop 0
	v_cndmask_b32_e32 v148, v148, v151, vcc
	v_rsq_f32_e32 v148, v148
	s_nop 0
	v_mul_f32_e32 v151, 0x45800000, v148
	v_cndmask_b32_e32 v148, v148, v151, vcc
	v_pk_mul_f32 v[154:155], v[148:149], v[154:155] op_sel_hi:[0,1]
	v_pk_mul_f32 v[142:143], v[148:149], v[142:143] op_sel_hi:[0,1]
	v_pk_mul_f32 v[154:155], v[18:19], v[154:155]
	v_pk_mul_f32 v[146:147], v[148:149], v[146:147] op_sel_hi:[0,1]
	v_pk_mul_f32 v[142:143], v[12:13], v[142:143]
	v_pk_mul_f32 v[140:141], v[148:149], v[140:141] op_sel_hi:[0,1]
	s_waitcnt vmcnt(11)
	v_pk_fma_f32 v[58:59], v[70:71], v[154:155], v[58:59]
	v_pk_mul_f32 v[146:147], v[20:21], v[146:147]
	v_pk_mul_f32 v[144:145], v[148:149], v[144:145] op_sel_hi:[0,1]
	s_waitcnt vmcnt(5)
	v_pk_fma_f32 v[68:69], v[80:81], v[142:143], v[68:69]
	v_pk_mul_f32 v[142:143], v[148:149], v[168:169] op_sel_hi:[0,1]
	v_pk_mul_f32 v[140:141], v[8:9], v[140:141]
	v_pk_fma_f32 v[60:61], v[72:73], v[146:147], v[60:61]
	v_pk_mul_f32 v[146:147], v[148:149], v[160:161] op_sel_hi:[0,1]
	v_pk_mul_f32 v[144:145], v[16:17], v[144:145]
	v_pk_mul_f32 v[142:143], v[6:7], v[142:143]
	s_waitcnt vmcnt(4)
	v_pk_fma_f32 v[56:57], v[84:85], v[140:141], v[56:57]
	v_pk_mul_f32 v[140:141], v[58:59], v[58:59]
	v_pk_mul_f32 v[146:147], v[14:15], v[146:147]
	v_pk_fma_f32 v[64:65], v[76:77], v[144:145], v[64:65]
	v_pk_mul_f32 v[144:145], v[148:149], v[166:167] op_sel_hi:[0,1]
	v_pk_fma_f32 v[54:55], v[82:83], v[142:143], v[54:55]
	v_pk_mul_f32 v[142:143], v[60:61], v[60:61]
	v_add_f32_e32 v140, v140, v141
	v_pk_fma_f32 v[62:63], v[74:75], v[146:147], v[62:63]
	v_pk_mul_f32 v[144:145], v[10:11], v[144:145]
	v_add_f32_e32 v140, v142, v140
	v_pk_fma_f32 v[66:67], v[78:79], v[144:145], v[66:67]
	v_pk_mul_f32 v[144:145], v[62:63], v[62:63]
	v_add_f32_e32 v140, v143, v140
	v_add_f32_e32 v140, v144, v140
	v_pk_mul_f32 v[146:147], v[64:65], v[64:65]
	v_add_f32_e32 v140, v145, v140
	v_add_f32_e32 v140, v146, v140
	global_store_dwordx4 v[152:153], v[58:61], off
	global_store_dwordx4 v[152:153], v[62:65], off offset:1024
	global_store_dwordx4 v[152:153], v[66:69], off offset:2048
	global_store_dwordx4 v[152:153], v[54:57], off offset:3072
	v_pk_mul_f32 v[152:153], v[66:67], v[66:67]
	v_add_f32_e32 v140, v147, v140
	v_add_f32_e32 v140, v152, v140
	v_pk_mul_f32 v[154:155], v[68:69], v[68:69]
	v_add_f32_e32 v140, v153, v140
	v_add_f32_e32 v140, v154, v140
	v_pk_mul_f32 v[156:157], v[54:55], v[54:55]
	v_add_f32_e32 v140, v155, v140
	v_add_f32_e32 v140, v156, v140
	v_pk_mul_f32 v[158:159], v[56:57], v[56:57]
	v_add_f32_e32 v140, v157, v140
	v_add_f32_e32 v140, v158, v140
	v_add_f32_e32 v140, v159, v140
	s_waitcnt vmcnt(7)
	v_pk_add_f32 v[144:145], v[106:107], 1.0 op_sel_hi:[1,0]
	v_lshl_add_u64 v[142:143], v[126:127], 0, v[122:123]
	v_add_f32_dpp v140, v140, v140 row_ror:1 row_mask:0xf bank_mask:0xf bound_ctrl:1
	v_lshl_add_u64 v[126:127], v[126:127], 0, s[12:13]
	v_mov_b64_e32 v[146:147], v[136:137]
	v_add_f32_dpp v140, v140, v140 row_ror:2 row_mask:0xf bank_mask:0xf bound_ctrl:1
	v_mov_b32_e32 v148, v2
	s_nop 0
	v_add_f32_dpp v140, v140, v140 row_ror:4 row_mask:0xf bank_mask:0xf bound_ctrl:1
	s_nop 1
	v_add_f32_dpp v140, v140, v140 row_ror:8 row_mask:0xf bank_mask:0xf bound_ctrl:1
	ds_bpermute_b32 v141, v149, v140
	s_waitcnt lgkmcnt(0)
	v_add_f32_e32 v140, v140, v141
	v_mov_b32_e32 v141, v140
	s_nop 1
	v_permlane32_swap_b32 v141, v140
	s_nop 1
	s_nop 0
	v_add_f32_e32 v140, v141, v140
	v_fmamk_f32 v140, v140, 0x3a800000, v1
	v_cmp_gt_f32_e32 vcc, s91, v140
	v_mul_f32_e32 v141, 0x4b800000, v140
	s_nop 0
	v_cndmask_b32_e32 v140, v140, v141, vcc
	v_rsq_f32_e32 v140, v140
	s_nop 0
	v_mul_f32_e32 v141, 0x45800000, v140
	v_cndmask_b32_e32 v140, v140, v141, vcc
	v_pk_mul_f32 v[58:59], v[58:59], v[140:141] op_sel_hi:[1,0]
	v_pk_mul_f32 v[60:61], v[60:61], v[140:141] op_sel_hi:[1,0]
	s_waitcnt vmcnt(4)
	v_pk_mul_f32 v[58:59], v[34:35], v[58:59]
	v_pk_mul_f32 v[60:61], v[36:37], v[60:61]
	v_pk_fma_f32 v[58:59], v[144:145], v[58:59], v[94:95]
	v_pk_add_f32 v[144:145], v[108:109], 1.0 op_sel_hi:[1,0]
	v_cvt_pk_bf16_f32 v58, v58, v59
	v_pk_fma_f32 v[60:61], v[144:145], v[60:61], v[96:97]
	v_pk_mul_f32 v[54:55], v[54:55], v[140:141] op_sel_hi:[1,0]
	v_cvt_pk_bf16_f32 v59, v60, v61
	v_add_co_u32_e32 v60, vcc, s0, v142
	v_pk_mul_f32 v[54:55], v[22:23], v[54:55]
	s_nop 0
	v_addc_co_u32_e32 v61, vcc, 0, v143, vcc
	global_store_dwordx2 v[60:61], v[58:59], off sc1
	v_pk_mul_f32 v[58:59], v[62:63], v[140:141] op_sel_hi:[1,0]
	v_pk_add_f32 v[62:63], v[86:87], 1.0 op_sel_hi:[1,0]
	v_pk_mul_f32 v[58:59], v[30:31], v[58:59]
	v_pk_mul_f32 v[56:57], v[56:57], v[140:141] op_sel_hi:[1,0]
	v_pk_fma_f32 v[58:59], v[62:63], v[58:59], v[98:99]
	v_pk_mul_f32 v[62:63], v[64:65], v[140:141] op_sel_hi:[1,0]
	v_pk_add_f32 v[64:65], v[88:89], 1.0 op_sel_hi:[1,0]
	v_pk_mul_f32 v[62:63], v[32:33], v[62:63]
	v_cvt_pk_bf16_f32 v58, v58, v59
	v_pk_fma_f32 v[62:63], v[64:65], v[62:63], v[100:101]
	v_pk_add_f32 v[64:65], v[92:93], 1.0 op_sel_hi:[1,0]
	v_cvt_pk_bf16_f32 v59, v62, v63
	global_store_dwordx2 v[60:61], v[58:59], off offset:512 sc1
	v_pk_mul_f32 v[58:59], v[66:67], v[140:141] op_sel_hi:[1,0]
	v_pk_add_f32 v[62:63], v[90:91], 1.0 op_sel_hi:[1,0]
	v_pk_mul_f32 v[58:59], v[26:27], v[58:59]
	v_pk_mul_f32 v[56:57], v[24:25], v[56:57]
	v_pk_fma_f32 v[58:59], v[62:63], v[58:59], v[114:115]
	v_pk_mul_f32 v[62:63], v[68:69], v[140:141] op_sel_hi:[1,0]
	v_cvt_pk_bf16_f32 v58, v58, v59
	v_pk_mul_f32 v[62:63], v[28:29], v[62:63]
	v_mov_b64_e32 v[68:69], v[48:49]
	v_pk_fma_f32 v[62:63], v[64:65], v[62:63], v[116:117]
	v_mov_b64_e32 v[140:141], v[130:131]
	v_cvt_pk_bf16_f32 v59, v62, v63
	global_store_dwordx2 v[60:61], v[58:59], off offset:1024 sc1
	v_pk_add_f32 v[58:59], v[102:103], 1.0 op_sel_hi:[1,0]
	v_mov_b64_e32 v[64:65], v[44:45]
	v_pk_fma_f32 v[54:55], v[58:59], v[54:55], v[110:111]
	v_pk_add_f32 v[58:59], v[104:105], 1.0 op_sel_hi:[1,0]
	v_cvt_pk_bf16_f32 v54, v54, v55
	v_pk_fma_f32 v[56:57], v[58:59], v[56:57], v[112:113]
	v_mov_b64_e32 v[142:143], v[132:133]
	v_cvt_pk_bf16_f32 v55, v56, v57
	global_store_dwordx2 v[60:61], v[54:55], off offset:1536 sc1
	v_mov_b64_e32 v[60:61], v[40:41]
	v_mov_b64_e32 v[56:57], v[52:53]
	v_mov_b64_e32 v[144:145], v[134:135]
	v_mov_b64_e32 v[58:59], v[38:39]
	v_mov_b64_e32 v[62:63], v[42:43]
	v_mov_b64_e32 v[66:67], v[46:47]
	v_mov_b64_e32 v[54:55], v[50:51]
	s_andn2_b64 exec, exec, s[6:7]
	s_cbranch_execz .LBB0_826
